# NSA selected branch non-diagonal blocks software pipelined: QK/exp2/PV of the three heads skewed so MFMA and VALU overlap inside a wave, exp2 and bf16 pack in place
# speedup vs baseline: 1.0110x; 1.0044x over previous
; DI void nsa_item(const Params& p, int bk, int qb, char* smem, float Mb) {
;     ...
;         while (j <= cur) {
;             const int jn = next_valid(j + 1, mn);
;             gload(jn <= cur ? jn : j);
;             const unsigned sub = (unsigned)(m >> (wave * 16)) & 0xffffu;
;             if (sub) {
;                 const char* kb_ = tb + bsel * 18432 + fr * 144 + fq * 16;
;                 bf16x8 kf[4][2], vf[4][2];
; #pragma unroll
;                 for (int k4 = 0; k4 < 4; ++k4) {
;                     kf[k4][0] = *(const bf16x8*)(kb_ + k4 * 16 * 144); kf[k4][1] = *(const bf16x8*)(kb_ + k4 * 16 * 144 + 64);
;                     vf[k4][0] = *(const bf16x8*)(kb_ + 9216 + k4 * 16 * 144); vf[k4][1] = *(const bf16x8*)(kb_ + 9216 + k4 * 16 * 144 + 64);
;                 }
;                 const bool mine = (sub >> fr) & 1u;
;                 const float Ml = mine ? Mb : 3.0e38f;
;                 const bool diag = (j == cur);
; #pragma unroll
;                 for (int g = 0; g < 3; ++g) {
;                     f32x4 st[4];
;                     st_from(kf, qf[g], st, -Ml);
;                     if (diag) {
; #pragma unroll
;                         for (int k4 = 0; k4 < 4; ++k4)
; #pragma unroll
;                             for (int ii = 0; ii < 4; ++ii) {
;                                 const float pv = (j * 64 + k4 * 16 + fq * 4 + ii <= tq) ? __builtin_amdgcn_exp2f(st[k4][ii]) : 0.f;
;                                 st[k4][ii] = pv; ls[g] += pv;
;                             }
;                     } else {
; #pragma unroll
;                         for (int k4 = 0; k4 < 4; ++k4)
; #pragma unroll
;                             for (int ii = 0; ii < 4; ++ii) { const float pv = __builtin_amdgcn_exp2f(st[k4][ii]); st[k4][ii] = pv; ls[g] += pv; }
;                     }
;                     pv_from(vf, st, o[g]);
;                 }
.LBB0_546:
	s_or_b64 exec, exec, s[8:9]
	v_cmp_gt_i32_e64 s[4:5], v242, v238
	v_mov_b32_e32 v207, v189
	v_mov_b32_e32 v205, v189
	v_cndmask_b32_e64 v72, v242, v245, s[4:5]
	v_ashrrev_i32_e32 v73, 31, v72
	v_lshlrev_b64 v[80:81], 13, v[72:73]
	v_lshl_add_u64 v[72:73], s[50:51], 0, v[80:81]
	v_lshl_add_u64 v[80:81], s[36:37], 0, v[80:81]
	v_lshl_add_u64 v[74:75], v[72:73], 0, v[188:189]
	v_lshl_add_u64 v[72:73], v[72:73], 0, v[206:207]
	v_lshl_add_u64 v[82:83], v[80:81], 0, v[188:189]
	v_lshl_add_u64 v[80:81], v[80:81], 0, v[206:207]
	v_lshl_add_u64 v[74:75], v[74:75], 0, v[204:205]
	v_lshl_add_u64 v[76:77], v[72:73], 0, v[204:205]
	v_lshl_add_u64 v[82:83], v[82:83], 0, v[204:205]
	v_lshl_add_u64 v[84:85], v[80:81], 0, v[204:205]
	global_load_dwordx4 v[72:75], v[74:75], off
	s_nop 0
	global_load_dwordx4 v[76:79], v[76:77], off
	s_nop 0
	global_load_dwordx4 v[80:83], v[82:83], off
	s_nop 0
	global_load_dwordx4 v[84:87], v[84:85], off
	v_lshrrev_b64 v[88:89], s93, v[88:89]
	v_cmp_ne_u32_sdwa s[6:7], v88, v189 src0_sel:WORD_0 src1_sel:DWORD
	s_and_saveexec_b64 s[12:13], s[6:7]
	s_cbranch_execz .LBB0_534
	s_mul_i32 s6, s22, 0x4800
	v_add_u32_e32 v116, s6, v239
	ds_read_b128 v[120:123], v116
	ds_read_b128 v[128:131], v116 offset:64
	ds_read_b128 v[132:135], v116 offset:2304
	ds_read_b128 v[136:139], v116 offset:2368
	ds_read_b128 v[144:147], v116 offset:4608
	v_and_b32_e32 v88, v240, v88
	v_cmp_ne_u32_e64 s[6:7], 0, v88
	ds_read_b128 v[148:151], v116 offset:4672
	ds_read_b128 v[152:155], v116 offset:6912
	v_cndmask_b32_e64 v124, v229, v235, s[6:7]
	v_mov_b32_e32 v125, v124
	v_mov_b32_e32 v126, v124
	v_mov_b32_e32 v127, v124
	v_cmp_ne_u32_e64 s[6:7], v245, v238
	s_nop 3
	s_and_b64 s[8:9], exec, s[6:7]
	s_cbranch_scc1 .Lsel_fast
	s_waitcnt lgkmcnt(4)
	v_mfma_f32_16x16x32_bf16 v[92:95], v[132:135], v[0:3], v[124:127]
	v_mfma_f32_16x16x32_bf16 v[88:91], v[120:123], v[0:3], v[124:127]
	s_waitcnt lgkmcnt(3)
	v_mfma_f32_16x16x32_bf16 v[176:179], v[136:139], v[4:7], v[92:95]
	s_waitcnt lgkmcnt(2)
	v_mfma_f32_16x16x32_bf16 v[92:95], v[144:147], v[0:3], v[124:127]
	v_mfma_f32_16x16x32_bf16 v[184:187], v[128:131], v[4:7], v[88:91]
	ds_read_b128 v[108:111], v116 offset:9216
	s_nop 1
	ds_read_b128 v[88:91], v116 offset:9280
	ds_read_b128 v[140:143], v116 offset:6976
	s_waitcnt lgkmcnt(3)
	v_mfma_f32_16x16x32_bf16 v[156:159], v[152:155], v[0:3], v[124:127]
	v_mfma_f32_16x16x32_bf16 v[168:171], v[148:151], v[4:7], v[92:95]
	s_nop 2
	ds_read_b128 v[92:95], v116 offset:11520
	ds_read_b128 v[96:99], v116 offset:11584
	ds_read_b128 v[100:103], v116 offset:13824
	ds_read_b128 v[104:107], v116 offset:13888
	ds_read_b128 v[112:115], v116 offset:16128
	ds_read_b128 v[116:119], v116 offset:16192
	s_waitcnt lgkmcnt(6)
	v_mfma_f32_16x16x32_bf16 v[160:163], v[140:143], v[4:7], v[156:159]
	s_and_saveexec_b64 s[8:9], s[6:7]
	s_xor_b64 s[8:9], exec, s[8:9]
	s_cbranch_execz .LBB0_549
	v_exp_f32_e32 v156, v184
	v_exp_f32_e32 v157, v185
	v_exp_f32_e32 v158, v186
	v_exp_f32_e32 v159, v187
	v_exp_f32_e32 v164, v176
	v_exp_f32_e32 v165, v177
	v_exp_f32_e32 v166, v178
	v_exp_f32_e32 v167, v179
	v_exp_f32_e32 v172, v168
	v_exp_f32_e32 v173, v169
	v_exp_f32_e32 v174, v170
	v_exp_f32_e32 v175, v171
	v_exp_f32_e32 v180, v160
	v_exp_f32_e32 v181, v161
	v_exp_f32_e32 v182, v162
	v_exp_f32_e32 v183, v163
	v_pk_add_f32 v[184:185], v[156:157], v[158:159]
	v_pk_add_f32 v[186:187], v[164:165], v[166:167]
	v_pk_add_f32 v[176:177], v[172:173], v[174:175]
	v_pk_add_f32 v[178:179], v[180:181], v[182:183]
	v_pk_add_f32 v[184:185], v[184:185], v[186:187]
	v_pk_add_f32 v[176:177], v[176:177], v[178:179]
	v_pk_add_f32 v[184:185], v[184:185], v[176:177]
	v_add_f32_e32 v244, v244, v184
	v_add_f32_e32 v244, v244, v185

; DI f32x4 mfma(bf16x8 a, bf16x8 b, f32x4 c) { return __builtin_amdgcn_mfma_f32_16x16x32_bf16(a, b, c, 0, 0, 0); }
; #pragma unroll
;     for (int k4 = 0; k4 < 4; ++k4) { f32x4 a = (f32x4){c0, c0, c0, c0}; a = mfma(kf[k4][0], qf[0], a); a = mfma(kf[k4][1], qf[1], a); st[k4] = a; }
; }
; DI void pv_from(const bf16x8 (&vf)[4][2], const f32x4 (&pt)[4], f32x4 (&o)[4]) {
;     const bf16x8 pb0 = pack2(pt[0], pt[1]), pb1 = pack2(pt[2], pt[3]);
; #pragma unroll
;     for (int dt = 0; dt < 4; ++dt) { o[dt] = mfma(vf[dt][0], pb0, o[dt]); o[dt] = mfma(vf[dt][1], pb1, o[dt]); }
; }
; DI void nsa_item(const Params& p, int bk, int qb, char* smem, float Mb) {
;     ...
; #pragma unroll
;                 for (int g = 0; g < 3; ++g) {
;                     f32x4 st[4];
;                     st_from(kf, qf[g], st, -Ml);
;                     if (diag) {
; #pragma unroll
;                         for (int k4 = 0; k4 < 4; ++k4)
; #pragma unroll
;                             for (int ii = 0; ii < 4; ++ii) {
;                                 const float pv = (j * 64 + k4 * 16 + fq * 4 + ii <= tq) ? __builtin_amdgcn_exp2f(st[k4][ii]) : 0.f;
;                                 st[k4][ii] = pv; ls[g] += pv;
;                             }
;                     } else {
; #pragma unroll
;                         for (int k4 = 0; k4 < 4; ++k4)
; #pragma unroll
;                             for (int ii = 0; ii < 4; ++ii) { const float pv = __builtin_amdgcn_exp2f(st[k4][ii]); st[k4][ii] = pv; ls[g] += pv; }
;                     }
;                     pv_from(vf, st, o[g]);
;                 }
.Lsel_fast:
	ds_read_b128 v[140:143], v116 offset:6976
	ds_read_b128 v[108:111], v116 offset:9216
	ds_read_b128 v[88:91], v116 offset:9280
	ds_read_b128 v[92:95], v116 offset:11520
	ds_read_b128 v[96:99], v116 offset:11584
	ds_read_b128 v[100:103], v116 offset:13824
	ds_read_b128 v[104:107], v116 offset:13888
	ds_read_b128 v[112:115], v116 offset:16128
	ds_read_b128 v[116:119], v116 offset:16192
	s_waitcnt lgkmcnt(8)
	v_mfma_f32_16x16x32_bf16 v[156:159], v[120:123], v[0:3], v[124:127]
	v_mfma_f32_16x16x32_bf16 v[164:167], v[132:135], v[0:3], v[124:127]
	v_mfma_f32_16x16x32_bf16 v[172:175], v[144:147], v[0:3], v[124:127]
	v_mfma_f32_16x16x32_bf16 v[180:183], v[152:155], v[0:3], v[124:127]
	v_mfma_f32_16x16x32_bf16 v[156:159], v[128:131], v[4:7], v[156:159]
	v_mfma_f32_16x16x32_bf16 v[164:167], v[136:139], v[4:7], v[164:167]
	v_mfma_f32_16x16x32_bf16 v[172:175], v[148:151], v[4:7], v[172:175]
	v_mfma_f32_16x16x32_bf16 v[180:183], v[140:143], v[4:7], v[180:183]
	v_mfma_f32_16x16x32_bf16 v[184:187], v[120:123], v[8:11], v[124:127]
	v_mfma_f32_16x16x32_bf16 v[176:179], v[132:135], v[8:11], v[124:127]
	v_mfma_f32_16x16x32_bf16 v[168:171], v[144:147], v[8:11], v[124:127]
	v_mfma_f32_16x16x32_bf16 v[160:163], v[152:155], v[8:11], v[124:127]
	s_nop 1
	v_mfma_f32_16x16x32_bf16 v[184:187], v[128:131], v[12:15], v[184:187]
	v_exp_f32_e32 v156, v156
	v_exp_f32_e32 v157, v157
	v_exp_f32_e32 v158, v158
	v_exp_f32_e32 v159, v159
	v_mfma_f32_16x16x32_bf16 v[176:179], v[136:139], v[12:15], v[176:179]
	v_exp_f32_e32 v164, v164
	v_exp_f32_e32 v165, v165
	v_exp_f32_e32 v166, v166
	v_exp_f32_e32 v167, v167
	v_mfma_f32_16x16x32_bf16 v[168:171], v[148:151], v[12:15], v[168:171]
	v_exp_f32_e32 v172, v172
	v_exp_f32_e32 v173, v173
	v_exp_f32_e32 v174, v174
	v_exp_f32_e32 v175, v175
	v_mfma_f32_16x16x32_bf16 v[160:163], v[140:143], v[12:15], v[160:163]
	v_exp_f32_e32 v180, v180
	v_exp_f32_e32 v181, v181
	v_exp_f32_e32 v182, v182
	v_exp_f32_e32 v183, v183
	v_pk_add_f32 v[254:255], v[156:157], v[158:159]
	v_pk_add_f32 v[254:255], v[254:255], v[164:165]
	v_pk_add_f32 v[254:255], v[254:255], v[166:167]
	v_cvt_pk_bf16_f32 v156, v156, v157
	v_cvt_pk_bf16_f32 v157, v158, v159
	v_cvt_pk_bf16_f32 v158, v164, v165
	v_cvt_pk_bf16_f32 v159, v166, v167
	v_pk_add_f32 v[164:165], v[172:173], v[174:175]
	v_pk_add_f32 v[164:165], v[164:165], v[180:181]
	v_pk_add_f32 v[164:165], v[164:165], v[182:183]
	v_cvt_pk_bf16_f32 v172, v172, v173
	v_cvt_pk_bf16_f32 v173, v174, v175
	v_cvt_pk_bf16_f32 v174, v180, v181
	v_cvt_pk_bf16_f32 v175, v182, v183
	v_pk_add_f32 v[254:255], v[254:255], v[164:165]
	v_add_f32_e32 v244, v244, v254
	v_add_f32_e32 v244, v244, v255
	s_waitcnt lgkmcnt(0)
; DI f32x4 mfma(bf16x8 a, bf16x8 b, f32x4 c) { return __builtin_amdgcn_mfma_f32_16x16x32_bf16(a, b, c, 0, 0, 0); }
; DI void pv_from(const bf16x8 (&vf)[4][2], const f32x4 (&pt)[4], f32x4 (&o)[4]) {
;     const bf16x8 pb0 = pack2(pt[0], pt[1]), pb1 = pack2(pt[2], pt[3]);
; #pragma unroll
;     for (int dt = 0; dt < 4; ++dt) { o[dt] = mfma(vf[dt][0], pb0, o[dt]); o[dt] = mfma(vf[dt][1], pb1, o[dt]); }
; }
; DI void nsa_item(const Params& p, int bk, int qb, char* smem, float Mb) {
;     ...
; #pragma unroll
;                 for (int g = 0; g < 3; ++g) {
;                     f32x4 st[4];
;                     st_from(kf, qf[g], st, -Ml);
;                     if (diag) {
; #pragma unroll
;                         for (int k4 = 0; k4 < 4; ++k4)
; #pragma unroll
;                             for (int ii = 0; ii < 4; ++ii) {
;                                 const float pv = (j * 64 + k4 * 16 + fq * 4 + ii <= tq) ? __builtin_amdgcn_exp2f(st[k4][ii]) : 0.f;
;                                 st[k4][ii] = pv; ls[g] += pv;
;                             }
;                     } else {
; #pragma unroll
;                         for (int k4 = 0; k4 < 4; ++k4)
; #pragma unroll
;                             for (int ii = 0; ii < 4; ++ii) { const float pv = __builtin_amdgcn_exp2f(st[k4][ii]); st[k4][ii] = pv; ls[g] += pv; }
;                     }
;                     pv_from(vf, st, o[g]);
;                 }
	s_nop 1
	v_mfma_f32_16x16x32_bf16 v[68:71], v[108:111], v[156:159], v[68:71]
	v_exp_f32_e32 v184, v184
	v_mfma_f32_16x16x32_bf16 v[64:67], v[92:95], v[156:159], v[64:67]
	v_exp_f32_e32 v185, v185
	v_mfma_f32_16x16x32_bf16 v[60:63], v[100:103], v[156:159], v[60:63]
	v_exp_f32_e32 v186, v186
	v_mfma_f32_16x16x32_bf16 v[56:59], v[112:115], v[156:159], v[56:59]
	v_exp_f32_e32 v187, v187
	v_mfma_f32_16x16x32_bf16 v[68:71], v[88:91], v[172:175], v[68:71]
	v_exp_f32_e32 v176, v176
	v_mfma_f32_16x16x32_bf16 v[64:67], v[96:99], v[172:175], v[64:67]
	v_exp_f32_e32 v177, v177
	v_mfma_f32_16x16x32_bf16 v[60:63], v[104:107], v[172:175], v[60:63]
	v_exp_f32_e32 v178, v178
	v_mfma_f32_16x16x32_bf16 v[56:59], v[116:119], v[172:175], v[56:59]
	v_exp_f32_e32 v179, v179
	v_mfma_f32_16x16x32_bf16 v[156:159], v[120:123], v[16:19], v[124:127]
	v_exp_f32_e32 v168, v168
	v_mfma_f32_16x16x32_bf16 v[164:167], v[132:135], v[16:19], v[124:127]
	v_exp_f32_e32 v169, v169
	v_mfma_f32_16x16x32_bf16 v[172:175], v[144:147], v[16:19], v[124:127]
	v_exp_f32_e32 v170, v170
	v_mfma_f32_16x16x32_bf16 v[180:183], v[152:155], v[16:19], v[124:127]
	v_exp_f32_e32 v171, v171
	v_mfma_f32_16x16x32_bf16 v[156:159], v[128:131], v[20:23], v[156:159]
	v_exp_f32_e32 v160, v160
	v_mfma_f32_16x16x32_bf16 v[164:167], v[136:139], v[20:23], v[164:167]
	v_exp_f32_e32 v161, v161
	v_mfma_f32_16x16x32_bf16 v[172:175], v[148:151], v[20:23], v[172:175]
	v_exp_f32_e32 v162, v162
	v_mfma_f32_16x16x32_bf16 v[180:183], v[140:143], v[20:23], v[180:183]
	v_exp_f32_e32 v163, v163
	v_pk_add_f32 v[254:255], v[184:185], v[186:187]
	v_pk_add_f32 v[254:255], v[254:255], v[176:177]
	v_pk_add_f32 v[254:255], v[254:255], v[178:179]
	v_cvt_pk_bf16_f32 v184, v184, v185
	v_cvt_pk_bf16_f32 v185, v186, v187
	v_cvt_pk_bf16_f32 v186, v176, v177
	v_cvt_pk_bf16_f32 v187, v178, v179
	v_pk_add_f32 v[176:177], v[168:169], v[170:171]
	v_pk_add_f32 v[176:177], v[176:177], v[160:161]
	v_pk_add_f32 v[176:177], v[176:177], v[162:163]
	v_cvt_pk_bf16_f32 v168, v168, v169
	v_cvt_pk_bf16_f32 v169, v170, v171
	v_cvt_pk_bf16_f32 v170, v160, v161
	v_cvt_pk_bf16_f32 v171, v162, v163
	v_pk_add_f32 v[254:255], v[254:255], v[176:177]
	v_add_f32_e32 v243, v243, v254
	v_add_f32_e32 v243, v243, v255
	s_nop 1
	v_mfma_f32_16x16x32_bf16 v[52:55], v[108:111], v[184:187], v[52:55]
	v_exp_f32_e32 v156, v156
	v_exp_f32_e32 v157, v157
	v_mfma_f32_16x16x32_bf16 v[48:51], v[92:95], v[184:187], v[48:51]
	v_exp_f32_e32 v158, v158
	v_exp_f32_e32 v159, v159
	v_mfma_f32_16x16x32_bf16 v[44:47], v[100:103], v[184:187], v[44:47]
	v_exp_f32_e32 v164, v164
	v_exp_f32_e32 v165, v165
	v_mfma_f32_16x16x32_bf16 v[40:43], v[112:115], v[184:187], v[40:43]
	v_exp_f32_e32 v166, v166
	v_exp_f32_e32 v167, v167
	v_mfma_f32_16x16x32_bf16 v[52:55], v[88:91], v[168:171], v[52:55]
	v_exp_f32_e32 v172, v172
	v_exp_f32_e32 v173, v173
	v_mfma_f32_16x16x32_bf16 v[48:51], v[96:99], v[168:171], v[48:51]
	v_exp_f32_e32 v174, v174
	v_exp_f32_e32 v175, v175
	v_mfma_f32_16x16x32_bf16 v[44:47], v[104:107], v[168:171], v[44:47]
	v_exp_f32_e32 v180, v180
	v_exp_f32_e32 v181, v181
	v_mfma_f32_16x16x32_bf16 v[40:43], v[116:119], v[168:171], v[40:43]
	v_exp_f32_e32 v182, v182
	v_exp_f32_e32 v183, v183
	v_pk_add_f32 v[254:255], v[156:157], v[158:159]
	v_pk_add_f32 v[254:255], v[254:255], v[164:165]
	v_pk_add_f32 v[254:255], v[254:255], v[166:167]
	v_cvt_pk_bf16_f32 v156, v156, v157
	v_cvt_pk_bf16_f32 v157, v158, v159
	v_cvt_pk_bf16_f32 v158, v164, v165
	v_cvt_pk_bf16_f32 v159, v166, v167
	v_pk_add_f32 v[164:165], v[172:173], v[174:175]
	v_pk_add_f32 v[164:165], v[164:165], v[180:181]
	v_pk_add_f32 v[164:165], v[164:165], v[182:183]
	v_cvt_pk_bf16_f32 v172, v172, v173
	v_cvt_pk_bf16_f32 v173, v174, v175
	v_cvt_pk_bf16_f32 v174, v180, v181
	v_cvt_pk_bf16_f32 v175, v182, v183
	v_pk_add_f32 v[254:255], v[254:255], v[164:165]
	v_add_f32_e32 v241, v241, v254
	v_add_f32_e32 v241, v241, v255
	s_nop 1
	v_mfma_f32_16x16x32_bf16 v[36:39], v[108:111], v[156:159], v[36:39]
	v_mfma_f32_16x16x32_bf16 v[32:35], v[92:95], v[156:159], v[32:35]
	v_mfma_f32_16x16x32_bf16 v[28:31], v[100:103], v[156:159], v[28:31]
	v_mfma_f32_16x16x32_bf16 v[24:27], v[112:115], v[156:159], v[24:27]
	v_mfma_f32_16x16x32_bf16 v[36:39], v[88:91], v[172:175], v[36:39]
	v_mfma_f32_16x16x32_bf16 v[32:35], v[96:99], v[172:175], v[32:35]
	v_mfma_f32_16x16x32_bf16 v[28:31], v[104:107], v[172:175], v[28:31]
	v_mfma_f32_16x16x32_bf16 v[24:27], v[116:119], v[172:175], v[24:27]
	s_branch .LBB0_534
